# attention: per-element validity via one unsigned range check (per-lane lo/hi per item) instead of 2 compares + 2 scalar ANDs + reloaded lane masks
# speedup vs baseline: 1.0069x; 1.0069x over previous
; __device__ __forceinline__ void attn_item(const Ctx& C, int it, int itn, u32x4 (&kv)[4], u32x4 (&vv)[4], u32x4 (&qv)[2]) {
;     ...
;     f32x4 sc[9];
; #pragma unroll
;     for (int kt = 0; kt < 9; ++kt) { const bf16_t* kr = Ks + (16 * (w + kt) + fr) * 72 + 8 * quad;
;         const bf16x8 k0 = *(const bf16x8*)kr, k1 = *(const bf16x8*)(kr + 32);
;         f32x4 z4 = {0.f, 0.f, 0.f, 0.f};
;         z4 = __builtin_amdgcn_mfma_f32_16x16x32_bf16(k0, qf[0], z4, 0, 0, 0);
;         sc[kt] = __builtin_amdgcn_mfma_f32_16x16x32_bf16(k1, qf[1], z4, 0, 0, 0); }
;     const int a = 16 * w + fr;
;     float mx = -1e30f;
; #pragma unroll
;     for (int kt = 0; kt < 9; ++kt)
; #pragma unroll
;         for (int rg = 0; rg < 4; ++rg) { const int cidx = 16 * (w + kt) + 4 * quad + rg, rel = cidx - 64 - a, ik = 128 * jb - 64 + cidx;
;             const bool valid = (rel >= -64) && (rel <= 64) && (ik >= 0) && (ik < n);
;             const int bi = rel < -64 ? 0 : (rel > 64 ? 128 : rel + 64);
;             const float s = valid ? sc[kt][rg] * 0.125f + bt[bi] : -1e30f;
;             sc[kt][rg] = s; mx = fmaxf(mx, s); }
.LBB0_359:
	s_waitcnt lgkmcnt(0)
	s_barrier
	ds_read_b32 v212, v98
	ds_read_b32 v213, v100
	ds_read_b32 v214, v102
	ds_read_b32 v215, v104
	ds_read_b32 v223, v106
	ds_read_b32 v228, v108
	ds_read_b32 v229, v110
	ds_read_b32 v230, v112
	ds_read_b32 v231, v114
	ds_read_b32 v232, v116
	ds_read_b32 v233, v118
	ds_read_b32 v234, v120
	ds_read_b32 v235, v122
	ds_read_b32 v236, v124
	ds_read_b32 v237, v126
	ds_read_b32 v238, v128
	ds_read_b32 v240, v130
	ds_read_b32 v241, v132
	ds_read_b32 v242, v134
	ds_read_b32 v243, v136
	ds_read_b32 v244, v138
	ds_read_b32 v245, v140
	ds_read_b32 v246, v142
	ds_read_b32 v247, v144
	ds_read_b32 v248, v146
	ds_read_b32 v249, v148
	ds_read_b32 v250, v150
	ds_read_b128 v[40:43], v85 offset:36864
	ds_read_b128 v[194:197], v85 offset:36928
	ds_read_b128 v[44:47], v87
	ds_read_b128 v[48:51], v87 offset:64
	s_waitcnt lgkmcnt(1)
	v_mfma_f32_16x16x32_bf16 v[44:47], v[44:47], v[40:43], 0
	s_lshr_b32 s0, 32, s52
	s_and_b32 s47, s36, 31
	s_add_i32 s0, s0, -1
	s_waitcnt lgkmcnt(0)
	v_mfma_f32_16x16x32_bf16 v[74:77], v[48:51], v[194:197], v[44:47]
	s_nop 2
	ds_read_b128 v[44:47], v173
	ds_read_b128 v[48:51], v173 offset:64
	s_and_b32 s0, s0, s47
	s_lshl_b32 s46, s0, 7
	s_waitcnt lgkmcnt(1)
	v_mfma_f32_16x16x32_bf16 v[44:47], v[44:47], v[40:43], 0
	s_sub_i32 s48, s46, 64
	v_add_u32_e32 v64, s48, v89
	v_readlane_b32 s0, v255, 7
	s_waitcnt lgkmcnt(0)
	v_mfma_f32_16x16x32_bf16 v[70:73], v[48:51], v[194:197], v[44:47]
	s_nop 2
	ds_read_b128 v[44:47], v174
	ds_read_b128 v[48:51], v174 offset:64
	s_lshr_b32 s53, 0x1000, s52
	v_cmp_lt_i32_e32 vcc, -1, v64
	s_waitcnt lgkmcnt(1)
	v_mfma_f32_16x16x32_bf16 v[44:47], v[44:47], v[40:43], 0
	v_readlane_b32 s1, v255, 8
	s_and_b64 s[0:1], s[0:1], vcc
	v_cmp_gt_i32_e32 vcc, s53, v64
	s_waitcnt lgkmcnt(0)
	v_mfma_f32_16x16x32_bf16 v[66:69], v[48:51], v[194:197], v[44:47]
	s_nop 2
	ds_read_b128 v[44:47], v175
	ds_read_b128 v[48:51], v175 offset:64
	s_and_b64 s[68:69], s[0:1], vcc
	s_waitcnt lgkmcnt(1)
	v_mfma_f32_16x16x32_bf16 v[44:47], v[44:47], v[40:43], 0
	s_waitcnt lgkmcnt(0)
	v_mfma_f32_16x16x32_bf16 v[60:63], v[48:51], v[194:197], v[44:47]
	s_nop 5
	ds_read_b128 v[44:47], v176
	ds_read_b128 v[48:51], v176 offset:64
	s_waitcnt lgkmcnt(1)
	v_mfma_f32_16x16x32_bf16 v[44:47], v[44:47], v[40:43], 0
	s_waitcnt lgkmcnt(0)
	v_mfma_f32_16x16x32_bf16 v[56:59], v[48:51], v[194:197], v[44:47]
	s_nop 5
	ds_read_b128 v[44:47], v177
	ds_read_b128 v[48:51], v177 offset:64
	s_waitcnt lgkmcnt(1)
	v_mfma_f32_16x16x32_bf16 v[44:47], v[44:47], v[40:43], 0
	s_waitcnt lgkmcnt(0)
	v_mfma_f32_16x16x32_bf16 v[52:55], v[48:51], v[194:197], v[44:47]
	s_nop 5
	ds_read_b128 v[44:47], v183
	ds_read_b128 v[48:51], v183 offset:64
	s_waitcnt lgkmcnt(1)
	v_mfma_f32_16x16x32_bf16 v[44:47], v[44:47], v[40:43], 0
	s_waitcnt lgkmcnt(0)
	v_mfma_f32_16x16x32_bf16 v[48:51], v[48:51], v[194:197], v[44:47]
	s_nop 5
	ds_read_b128 v[44:47], v192
	ds_read_b128 v[198:201], v192 offset:64
	s_waitcnt lgkmcnt(1)
	v_mfma_f32_16x16x32_bf16 v[44:47], v[44:47], v[40:43], 0
	s_waitcnt lgkmcnt(0)
	v_mfma_f32_16x16x32_bf16 v[44:47], v[198:201], v[194:197], v[44:47]
	ds_read_b128 v[198:201], v193
	ds_read_b128 v[202:205], v193 offset:64
	s_waitcnt lgkmcnt(1)
	v_mfma_f32_16x16x32_bf16 v[40:43], v[198:201], v[40:43], 0
	s_waitcnt lgkmcnt(0)
	v_mfma_f32_16x16x32_bf16 v[40:43], v[202:205], v[194:197], v[40:43]
	v_lshrrev_b32_e32 v178, 6, v224
	v_lshlrev_b32_e32 v178, 4, v178
	v_and_b32_e32 v179, 15, v224
	v_add_u32_e32 v179, v178, v179
	s_sub_i32 s0, 0, s48
	v_max_i32_e32 v180, s0, v179
	s_sub_i32 s1, s53, s48
	s_add_i32 s1, s1, -1
	v_add_u32_e32 v179, 0x80, v179
	v_min_i32_e32 v181, s1, v179
	v_bfe_u32 v179, v224, 4, 2
	v_lshl_add_u32 v178, v179, 2, v178
	v_sub_u32_e32 v188, v178, v180
	v_sub_u32_e32 v189, v181, v180
	v_mov_b32_e32 v179, 0xf149f2ca
	v_add_u32_e32 v190, 0, v188
	v_cmp_ge_u32_e32 vcc, v189, v190
	v_fmac_f32_e32 v212, 0x3e000000, v74
	v_add_u32_e32 v191, 1, v188
	v_cndmask_b32_e32 v195, v179, v212, vcc
	ds_read_b32 v212, v152
	v_cmp_ge_u32_e32 vcc, v189, v191
	v_fmac_f32_e32 v213, 0x3e000000, v75
	v_add_u32_e32 v190, 2, v188
	v_cndmask_b32_e32 v91, v179, v213, vcc
	ds_read_b32 v213, v154
	v_cmp_ge_u32_e32 vcc, v189, v190
	v_fmac_f32_e32 v214, 0x3e000000, v76
	v_add_u32_e32 v191, 3, v188
	v_cndmask_b32_e32 v194, v179, v214, vcc
	ds_read_b32 v214, v156
	v_cmp_ge_u32_e32 vcc, v189, v191
	v_fmac_f32_e32 v215, 0x3e000000, v77
	v_add_u32_e32 v190, 16, v188
	v_cndmask_b32_e32 v79, v179, v215, vcc
	ds_read_b32 v215, v158
	v_cmp_ge_u32_e32 vcc, v189, v190
	v_fmac_f32_e32 v223, 0x3e000000, v70
	v_add_u32_e32 v191, 17, v188
	v_cndmask_b32_e32 v74, v179, v223, vcc
	ds_read_b32 v223, v160
	v_cmp_ge_u32_e32 vcc, v189, v191
	v_fmac_f32_e32 v228, 0x3e000000, v71
	v_add_u32_e32 v190, 18, v188
	v_cndmask_b32_e32 v64, v179, v228, vcc
	ds_read_b32 v228, v162
	v_cmp_ge_u32_e32 vcc, v189, v190
	v_fmac_f32_e32 v229, 0x3e000000, v72
	v_add_u32_e32 v191, 19, v188
	v_cndmask_b32_e32 v75, v179, v229, vcc
	ds_read_b32 v229, v164
	v_cmp_ge_u32_e32 vcc, v189, v191
	v_fmac_f32_e32 v230, 0x3e000000, v73
	v_add_u32_e32 v190, 32, v188
	v_cndmask_b32_e32 v70, v179, v230, vcc
	ds_read_b32 v230, v166
	v_cmp_ge_u32_e32 vcc, v189, v190
	v_fmac_f32_e32 v231, 0x3e000000, v66
	v_add_u32_e32 v191, 33, v188
	v_cndmask_b32_e32 v72, v179, v231, vcc
	ds_read_b32 v231, v168
	v_cmp_ge_u32_e32 vcc, v189, v191
	v_fmac_f32_e32 v232, 0x3e000000, v67
	v_add_u32_e32 v190, 34, v188
	v_cndmask_b32_e32 v71, v179, v232, vcc
	v_cmp_ge_u32_e32 vcc, v189, v190
	v_fmac_f32_e32 v233, 0x3e000000, v68
	v_add_u32_e32 v191, 35, v188
	v_cndmask_b32_e32 v73, v179, v233, vcc
	v_cmp_ge_u32_e32 vcc, v189, v191
; __device__ __forceinline__ void attn_item(const Ctx& C, int it, int itn, u32x4 (&kv)[4], u32x4 (&vv)[4], u32x4 (&qv)[2]) {
;     ...
;     const int a = 16 * w + fr;
;     float mx = -1e30f;
; #pragma unroll
;     for (int kt = 0; kt < 9; ++kt)
; #pragma unroll
;         for (int rg = 0; rg < 4; ++rg) { const int cidx = 16 * (w + kt) + 4 * quad + rg, rel = cidx - 64 - a, ik = 128 * jb - 64 + cidx;
;             const bool valid = (rel >= -64) && (rel <= 64) && (ik >= 0) && (ik < n);
;             const int bi = rel < -64 ? 0 : (rel > 64 ? 128 : rel + 64);
;             const float s = valid ? sc[kt][rg] * 0.125f + bt[bi] : -1e30f;
;             sc[kt][rg] = s; mx = fmaxf(mx, s); }
;     mx = fmaxf(mx, __shfl_xor(mx, 16)); mx = fmaxf(mx, __shfl_xor(mx, 32));
;     float lsum = 0.f;
; #pragma unroll
;     for (int kt = 0; kt < 9; ++kt)
; #pragma unroll
;         for (int rg = 0; rg < 4; ++rg) { const float s = sc[kt][rg]; const float p = (s > -1e29f) ? __expf(s - mx) : 0.f; sc[kt][rg] = p; lsum += p; }
	v_fmac_f32_e32 v234, 0x3e000000, v69
	v_add_u32_e32 v190, 48, v188
	v_cndmask_b32_e32 v66, v179, v234, vcc
	v_cmp_ge_u32_e32 vcc, v189, v190
	v_fmac_f32_e32 v235, 0x3e000000, v60
	v_add_u32_e32 v191, 49, v188
	v_cndmask_b32_e32 v69, v179, v235, vcc
	v_cmp_ge_u32_e32 vcc, v189, v191
	v_fmac_f32_e32 v236, 0x3e000000, v61
	v_add_u32_e32 v190, 50, v188
	v_cndmask_b32_e32 v67, v179, v236, vcc
	v_cmp_ge_u32_e32 vcc, v189, v190
	v_fmac_f32_e32 v237, 0x3e000000, v62
	v_add_u32_e32 v191, 51, v188
	v_cndmask_b32_e32 v68, v179, v237, vcc
	v_cmp_ge_u32_e32 vcc, v189, v191
	v_fmac_f32_e32 v238, 0x3e000000, v63
	v_add_u32_e32 v190, 64, v188
	v_cndmask_b32_e32 v60, v179, v238, vcc
	v_cmp_ge_u32_e32 vcc, v189, v190
	v_fmac_f32_e32 v240, 0x3e000000, v56
	v_add_u32_e32 v191, 0x41, v188
	v_cndmask_b32_e32 v62, v179, v240, vcc
	v_cmp_ge_u32_e32 vcc, v189, v191
	v_fmac_f32_e32 v241, 0x3e000000, v57
	v_add_u32_e32 v190, 0x42, v188
	v_cndmask_b32_e32 v61, v179, v241, vcc
	v_cmp_ge_u32_e32 vcc, v189, v190
	v_fmac_f32_e32 v242, 0x3e000000, v58
	v_add_u32_e32 v191, 0x43, v188
	v_cndmask_b32_e32 v63, v179, v242, vcc
	v_cmp_ge_u32_e32 vcc, v189, v191
	v_fmac_f32_e32 v243, 0x3e000000, v59
	v_add_u32_e32 v190, 0x50, v188
	v_cndmask_b32_e32 v57, v179, v243, vcc
	v_cmp_ge_u32_e32 vcc, v189, v190
	v_fmac_f32_e32 v244, 0x3e000000, v52
	v_add_u32_e32 v191, 0x51, v188
	v_cndmask_b32_e32 v59, v179, v244, vcc
	v_cmp_ge_u32_e32 vcc, v189, v191
	v_fmac_f32_e32 v245, 0x3e000000, v53
	v_add_u32_e32 v190, 0x52, v188
	v_cndmask_b32_e32 v56, v179, v245, vcc
	v_cmp_ge_u32_e32 vcc, v189, v190
	v_fmac_f32_e32 v246, 0x3e000000, v54
	v_add_u32_e32 v191, 0x53, v188
	v_cndmask_b32_e32 v58, v179, v246, vcc
	v_cmp_ge_u32_e32 vcc, v189, v191
	v_fmac_f32_e32 v247, 0x3e000000, v55
	v_add_u32_e32 v190, 0x60, v188
	v_cndmask_b32_e32 v53, v179, v247, vcc
	v_cmp_ge_u32_e32 vcc, v189, v190
	v_fmac_f32_e32 v248, 0x3e000000, v48
	v_add_u32_e32 v191, 0x61, v188
	v_cndmask_b32_e32 v55, v179, v248, vcc
	v_cmp_ge_u32_e32 vcc, v189, v191
	v_fmac_f32_e32 v249, 0x3e000000, v49
	v_add_u32_e32 v190, 0x62, v188
	v_cndmask_b32_e32 v52, v179, v249, vcc
	v_cmp_ge_u32_e32 vcc, v189, v190
	v_fmac_f32_e32 v250, 0x3e000000, v50
	v_add_u32_e32 v191, 0x63, v188
	v_cndmask_b32_e32 v54, v179, v250, vcc
	s_waitcnt lgkmcnt(0)
	v_cmp_ge_u32_e32 vcc, v189, v191
	v_fmac_f32_e32 v212, 0x3e000000, v51
	v_add_u32_e32 v190, 0x70, v188
	v_cndmask_b32_e32 v49, v179, v212, vcc
	v_cmp_ge_u32_e32 vcc, v189, v190
	v_fmac_f32_e32 v213, 0x3e000000, v44
	v_add_u32_e32 v191, 0x71, v188
	v_cndmask_b32_e32 v50, v179, v213, vcc
	v_cmp_ge_u32_e32 vcc, v189, v191
	v_fmac_f32_e32 v214, 0x3e000000, v45
	v_add_u32_e32 v190, 0x72, v188
	v_cndmask_b32_e32 v48, v179, v214, vcc
	v_cmp_ge_u32_e32 vcc, v189, v190
	v_fmac_f32_e32 v215, 0x3e000000, v46
	v_add_u32_e32 v191, 0x73, v188
	v_cndmask_b32_e32 v45, v179, v215, vcc
	v_cmp_ge_u32_e32 vcc, v189, v191
	v_fmac_f32_e32 v223, 0x3e000000, v47
	v_add_u32_e32 v190, 0x80, v188
	v_cndmask_b32_e32 v44, v179, v223, vcc
	v_cmp_ge_u32_e32 vcc, v189, v190
	v_fmac_f32_e32 v228, 0x3e000000, v40
	v_add_u32_e32 v191, 0x81, v188
	v_cndmask_b32_e32 v47, v179, v228, vcc
	v_cmp_ge_u32_e32 vcc, v189, v191
	v_fmac_f32_e32 v229, 0x3e000000, v41
	v_add_u32_e32 v190, 0x82, v188
	v_cndmask_b32_e32 v46, v179, v229, vcc
	v_cmp_ge_u32_e32 vcc, v189, v190
	v_fmac_f32_e32 v230, 0x3e000000, v42
	v_add_u32_e32 v191, 0x83, v188
	v_cndmask_b32_e32 v51, v179, v230, vcc
	v_cmp_ge_u32_e32 vcc, v189, v191
	v_fmac_f32_e32 v231, 0x3e000000, v43
	s_nop 0
	v_cndmask_b32_e32 v41, v179, v231, vcc
	s_mov_b32 s0, 0xf149f2ca
	v_max3_f32 v40, v195, s0, v91
	v_max3_f32 v40, v40, v194, v79
	v_max3_f32 v40, v40, v74, v64
	v_max3_f32 v40, v40, v75, v70
	v_max3_f32 v40, v40, v72, v71
	v_max3_f32 v40, v40, v73, v66
	v_max3_f32 v40, v40, v69, v67
	v_max3_f32 v40, v40, v68, v60
	v_max3_f32 v40, v40, v62, v61
	v_max3_f32 v40, v40, v63, v57
	v_max3_f32 v40, v40, v59, v56
	v_max3_f32 v40, v40, v58, v53
	v_max3_f32 v40, v40, v55, v52
	v_max3_f32 v40, v40, v54, v49
	v_max3_f32 v40, v40, v50, v48
	v_max3_f32 v40, v40, v45, v44
	v_max3_f32 v40, v40, v47, v46
	v_max3_f32 v40, v40, v51, v41
	ds_bpermute_b32 v42, v169, v40
	s_mov_b32 s1, 0xefa18f08
	s_sub_i32 s0, 5, s52
	s_lshr_b32 s0, s47, s0
	s_waitcnt lgkmcnt(0)
	v_max_f32_e32 v42, v42, v42
	v_max_f32_e32 v40, v40, v42
	ds_bpermute_b32 v42, v170, v40
	s_waitcnt lgkmcnt(0)
	v_max_f32_e32 v42, v42, v42
	v_max_f32_e32 v42, v40, v42
	v_sub_f32_e32 v40, v195, v42
	v_mul_f32_e32 v40, 0x3fb8aa3b, v40
	v_sub_f32_e32 v43, v91, v42
	v_exp_f32_e32 v40, v40
	v_mul_f32_e32 v43, 0x3fb8aa3b, v43
	v_exp_f32_e32 v43, v43
	v_add_f32_e32 v76, 0, v40
	s_nop 0
	v_add_f32_e32 v77, v43, v76
	v_sub_f32_e32 v76, v194, v42
	v_mul_f32_e32 v76, 0x3fb8aa3b, v76
	v_exp_f32_e32 v76, v76
	v_cvt_pk_bf16_f32 v196, v40, v43
	s_nop 0
	v_add_f32_e32 v91, v76, v77
	v_sub_f32_e32 v77, v79, v42
	v_mul_f32_e32 v77, 0x3fb8aa3b, v77
	v_exp_f32_e32 v77, v77
	s_nop 1
	v_sub_f32_e32 v74, v74, v42
	v_mul_f32_e32 v74, 0x3fb8aa3b, v74
	v_exp_f32_e32 v74, v74
	v_add_f32_e32 v79, v77, v91
	v_cvt_pk_bf16_f32 v197, v76, v77
	v_sub_f32_e32 v64, v64, v42
	v_mul_f32_e32 v64, 0x3fb8aa3b, v64
	v_exp_f32_e32 v64, v64
	v_add_f32_e32 v91, v74, v79
	v_mov_b32_e32 v79, v64
	v_sub_f32_e32 v75, v75, v42
	v_mul_f32_e32 v75, 0x3fb8aa3b, v75
	v_exp_f32_e32 v75, v75
	v_add_f32_e32 v64, v79, v91
	v_cvt_pk_bf16_f32 v198, v74, v79
	v_sub_f32_e32 v70, v70, v42
	v_mul_f32_e32 v70, 0x3fb8aa3b, v70
	v_exp_f32_e32 v70, v70
	v_add_f32_e32 v64, v75, v64
	v_mov_b32_e32 v91, v70
	v_add_f32_e32 v70, v91, v64
	v_sub_f32_e32 v64, v72, v42
	v_mul_f32_e32 v64, 0x3fb8aa3b, v64
	v_exp_f32_e32 v64, v64
	v_cvt_pk_bf16_f32 v199, v75, v91
	ds_read_b64_tr_b16 v[76:77], v171 offset:57600
	ds_read_b64_tr_b16 v[74:75], v171 offset:55296
	ds_read_b64_tr_b16 v[200:201], v171 offset:55328
	v_add_f32_e32 v72, v64, v70
	v_sub_f32_e32 v70, v71, v42
	v_mul_f32_e32 v70, 0x3fb8aa3b, v70
	v_sub_f32_e32 v71, v73, v42
	v_exp_f32_e32 v70, v70
	v_mul_f32_e32 v71, 0x3fb8aa3b, v71
	v_exp_f32_e32 v71, v71
	ds_read_b64_tr_b16 v[202:203], v171 offset:57632
	v_add_f32_e32 v72, v70, v72
	ds_read_b64_tr_b16 v[204:205], v171 offset:55360
	ds_read_b64_tr_b16 v[206:207], v171 offset:57664
	v_sub_f32_e32 v66, v66, v42
	v_mul_f32_e32 v66, 0x3fb8aa3b, v66
	v_exp_f32_e32 v66, v66
	v_add_f32_e32 v72, v71, v72
	ds_read_b64_tr_b16 v[208:209], v171 offset:55392
	ds_read_b64_tr_b16 v[210:211], v171 offset:57696
	s_waitcnt lgkmcnt(6)
; __device__ __forceinline__ unsigned cvt_pk_bf16(float lo, float hi) { f32x2_t v = {lo, hi}; bf2_t r = __builtin_convertvector(v, bf2_t); return __builtin_bit_cast(unsigned, r); }
; __device__ __forceinline__ s16x4_t lds_tr_b64(const bf16_t* p) { return __builtin_amdgcn_ds_read_tr16_b64_v4i16((LAS s16x4_t*)p); }
; __device__ __forceinline__ void attn_item(const Ctx& C, int it, int itn, u32x4 (&kv)[4], u32x4 (&vv)[4], u32x4 (&qv)[2]) {
;     ...
;     float lsum = 0.f;
; #pragma unroll
;     for (int kt = 0; kt < 9; ++kt)
; #pragma unroll
;         for (int rg = 0; rg < 4; ++rg) { const float s = sc[kt][rg]; const float p = (s > -1e29f) ? __expf(s - mx) : 0.f; sc[kt][rg] = p; lsum += p; }
;     lsum += __shfl_xor(lsum, 16); lsum += __shfl_xor(lsum, 32);
;     f32x4 oo[4];
; #pragma unroll
;     for (int dt = 0; dt < 4; ++dt) oo[dt] = (f32x4){0.f, 0.f, 0.f, 0.f};
; #pragma unroll
;     for (int pp = 0; pp < 5; ++pp) { const int ktA = 2 * pp, ktB = 2 * pp + 1, ktBc = ktB < 9 ? ktB : 8;
;         union { bf16x8 v; unsigned u[4]; } pf;
;         pf.u[0] = cvt_pk_bf16(sc[ktA][0], sc[ktA][1]); pf.u[1] = cvt_pk_bf16(sc[ktA][2], sc[ktA][3]);
;         if (ktB < 9) { pf.u[2] = cvt_pk_bf16(sc[ktBc][0], sc[ktBc][1]); pf.u[3] = cvt_pk_bf16(sc[ktBc][2], sc[ktBc][3]); } else { pf.u[2] = 0u; pf.u[3] = 0u; }
; #pragma unroll
;         for (int dt = 0; dt < 4; ++dt) { const bf16_t* vr = Vs + (16 * w + 4 * quad + (fr >> 2)) * 72 + 16 * dt + 4 * (fr & 3);
;             union { bf16x8 v; s16x4_t h[2]; } vf; vf.h[0] = lds_tr_b64(vr + 16 * ktA * 72); vf.h[1] = lds_tr_b64(vr + 16 * ktBc * 72);
;             oo[dt] = __builtin_amdgcn_mfma_f32_16x16x32_bf16(vf.v, pf.v, oo[dt], 0, 0, 0); } }
	v_mfma_f32_16x16x32_bf16 v[74:77], v[74:77], v[196:199], 0
	v_sub_f32_e32 v69, v69, v42
	v_mul_f32_e32 v69, 0x3fb8aa3b, v69
	v_exp_f32_e32 v69, v69
	v_add_f32_e32 v72, v66, v72
	s_waitcnt lgkmcnt(4)
	v_mfma_f32_16x16x32_bf16 v[200:203], v[200:203], v[196:199], 0
	v_mov_b32_e32 v91, v65
	v_sub_f32_e32 v67, v67, v42
	v_mul_f32_e32 v67, 0x3fb8aa3b, v67
	v_exp_f32_e32 v67, v67
	v_add_f32_e32 v72, v69, v72
	s_waitcnt lgkmcnt(2)
	v_mfma_f32_16x16x32_bf16 v[204:207], v[204:207], v[196:199], 0
	v_sub_f32_e32 v68, v68, v42
	v_mul_f32_e32 v68, 0x3fb8aa3b, v68
	v_exp_f32_e32 v68, v68
	v_add_f32_e32 v72, v67, v72
	s_waitcnt lgkmcnt(0)
	v_mfma_f32_16x16x32_bf16 v[196:199], v[208:211], v[196:199], 0
	v_cvt_pk_bf16_f32 v209, v71, v66
	v_sub_f32_e32 v60, v60, v42
	v_mul_f32_e32 v60, 0x3fb8aa3b, v60
	v_exp_f32_e32 v60, v60
	v_add_f32_e32 v73, v68, v72
	v_cvt_pk_bf16_f32 v210, v69, v67
	v_cvt_pk_bf16_f32 v208, v64, v70
	v_mov_b32_e32 v72, v60
	v_sub_f32_e32 v60, v62, v42
	v_mul_f32_e32 v60, 0x3fb8aa3b, v60
	v_exp_f32_e32 v60, v60
	v_add_f32_e32 v73, v72, v73
	v_cvt_pk_bf16_f32 v211, v68, v72
	v_sub_f32_e32 v61, v61, v42
	v_mul_f32_e32 v61, 0x3fb8aa3b, v61
	v_exp_f32_e32 v61, v61
	v_add_f32_e32 v62, v60, v73
	ds_read_b64_tr_b16 v[66:67], v171 offset:59904
	ds_read_b64_tr_b16 v[68:69], v171 offset:62208
	s_waitcnt lgkmcnt(0)
	v_mfma_f32_16x16x32_bf16 v[66:69], v[66:69], v[208:211], v[74:77]
	v_add_f32_e32 v73, v61, v62
	v_sub_f32_e32 v62, v63, v42
	v_mul_f32_e32 v62, 0x3fb8aa3b, v62
	v_exp_f32_e32 v62, v62
	ds_read_b64_tr_b16 v[74:75], v171 offset:59936
	ds_read_b64_tr_b16 v[76:77], v171 offset:62240
	s_waitcnt lgkmcnt(0)
	v_mfma_f32_16x16x32_bf16 v[74:77], v[74:77], v[208:211], v[200:203]
	v_sub_f32_e32 v57, v57, v42
	v_mul_f32_e32 v57, 0x3fb8aa3b, v57
	v_exp_f32_e32 v57, v57
	v_add_f32_e32 v63, v62, v73
	ds_read_b64_tr_b16 v[200:201], v171 offset:59968
	ds_read_b64_tr_b16 v[202:203], v171 offset:62272
	s_waitcnt lgkmcnt(0)
	v_mfma_f32_16x16x32_bf16 v[200:203], v[200:203], v[208:211], v[204:207]
	v_sub_f32_e32 v59, v59, v42
	v_mul_f32_e32 v59, 0x3fb8aa3b, v59
	v_exp_f32_e32 v59, v59
	v_add_f32_e32 v63, v57, v63
	ds_read_b64_tr_b16 v[204:205], v171 offset:60000
	ds_read_b64_tr_b16 v[206:207], v171 offset:62304
	v_cvt_pk_bf16_f32 v60, v60, v61
	v_sub_f32_e32 v56, v56, v42
	v_mul_f32_e32 v56, 0x3fb8aa3b, v56
	v_exp_f32_e32 v56, v56
	v_add_f32_e32 v63, v59, v63
	v_cvt_pk_bf16_f32 v61, v62, v57
	s_waitcnt lgkmcnt(0)
	v_mfma_f32_16x16x32_bf16 v[196:199], v[204:207], v[208:211], v[196:199]
	v_sub_f32_e32 v58, v58, v42
	v_mul_f32_e32 v58, 0x3fb8aa3b, v58
	v_exp_f32_e32 v58, v58
	v_add_f32_e32 v63, v56, v63
	v_cvt_pk_bf16_f32 v62, v59, v56
	v_mov_b32_e32 v64, v65
	v_sub_f32_e32 v53, v53, v42
	v_mul_f32_e32 v53, 0x3fb8aa3b, v53
	v_exp_f32_e32 v53, v53
	v_add_f32_e32 v73, v58, v63
	v_mov_b32_e32 v63, v53
	v_sub_f32_e32 v53, v55, v42
	v_mul_f32_e32 v53, 0x3fb8aa3b, v53
	v_exp_f32_e32 v53, v53
	v_add_f32_e32 v73, v63, v73
	v_cvt_pk_bf16_f32 v63, v58, v63
	v_sub_f32_e32 v52, v52, v42
	v_mul_f32_e32 v52, 0x3fb8aa3b, v52
	v_exp_f32_e32 v52, v52
	ds_read_b64_tr_b16 v[56:57], v171 offset:64512
	ds_read_b64_tr_b16 v[58:59], v172 offset:11520
	ds_read_b64_tr_b16 v[70:71], v172 offset:11552
	v_add_f32_e32 v55, v53, v73
	s_waitcnt lgkmcnt(1)
	v_mfma_f32_16x16x32_bf16 v[56:59], v[56:59], v[60:63], v[66:69]
	v_sub_f32_e32 v54, v54, v42
	v_mul_f32_e32 v54, 0x3fb8aa3b, v54
	v_exp_f32_e32 v54, v54
	v_add_f32_e32 v55, v52, v55
	ds_read_b64_tr_b16 v[68:69], v171 offset:64544
	s_waitcnt lgkmcnt(0)
	v_mfma_f32_16x16x32_bf16 v[66:69], v[68:71], v[60:63], v[74:77]
	v_sub_f32_e32 v49, v49, v42
	v_mul_f32_e32 v49, 0x3fb8aa3b, v49
	v_exp_f32_e32 v49, v49
	v_add_f32_e32 v55, v54, v55
	ds_read_b64_tr_b16 v[74:75], v171 offset:64576
	ds_read_b64_tr_b16 v[76:77], v172 offset:11584
	s_waitcnt lgkmcnt(0)
	v_mfma_f32_16x16x32_bf16 v[74:77], v[74:77], v[60:63], v[200:203]
	v_sub_f32_e32 v50, v50, v42
	v_mul_f32_e32 v50, 0x3fb8aa3b, v50
	v_exp_f32_e32 v50, v50
	v_add_f32_e32 v55, v49, v55
	ds_read_b64_tr_b16 v[200:201], v171 offset:64608
	ds_read_b64_tr_b16 v[202:203], v172 offset:11616
	v_cvt_pk_bf16_f32 v52, v53, v52
	v_sub_f32_e32 v48, v48, v42
	v_mul_f32_e32 v48, 0x3fb8aa3b, v48
	v_exp_f32_e32 v48, v48
	v_add_f32_e32 v73, v50, v55
	v_cvt_pk_bf16_f32 v53, v54, v49
	s_waitcnt lgkmcnt(0)
	v_mfma_f32_16x16x32_bf16 v[60:63], v[200:203], v[60:63], v[196:199]
	v_mov_b32_e32 v55, v48
	v_sub_f32_e32 v45, v45, v42
	v_mul_f32_e32 v45, 0x3fb8aa3b, v45
	v_exp_f32_e32 v45, v45
	v_add_f32_e32 v48, v55, v73
	v_cvt_pk_bf16_f32 v54, v50, v55
	v_mov_b32_e32 v73, v45
	v_sub_f32_e32 v44, v44, v42
	v_mul_f32_e32 v44, 0x3fb8aa3b, v44
	v_exp_f32_e32 v44, v44
	v_add_f32_e32 v45, v73, v48
	v_mov_b32_e32 v194, v44
	v_add_f32_e32 v44, v194, v45
	v_sub_f32_e32 v45, v47, v42
	v_cvt_pk_bf16_f32 v55, v73, v194
	ds_read_b64_tr_b16 v[70:71], v172 offset:13824
	ds_read_b64_tr_b16 v[72:73], v172 offset:16128
	v_mul_f32_e32 v45, 0x3fb8aa3b, v45
	v_exp_f32_e32 v45, v45
	s_waitcnt lgkmcnt(0)
; __device__ __forceinline__ unsigned cvt_pk_bf16(float lo, float hi) { f32x2_t v = {lo, hi}; bf2_t r = __builtin_convertvector(v, bf2_t); return __builtin_bit_cast(unsigned, r); }
; __device__ __forceinline__ s16x4_t lds_tr_b64(const bf16_t* p) { return __builtin_amdgcn_ds_read_tr16_b64_v4i16((LAS s16x4_t*)p); }
;     __device__ __forceinline__ float* fp(size_t off) const { return (float*)(ws + off); }
; __device__ __forceinline__ void attn_item(const Ctx& C, int it, int itn, u32x4 (&kv)[4], u32x4 (&vv)[4], u32x4 (&qv)[2]) {
;     ...
;     lsum += __shfl_xor(lsum, 16); lsum += __shfl_xor(lsum, 32);
;     f32x4 oo[4];
; #pragma unroll
;     for (int dt = 0; dt < 4; ++dt) oo[dt] = (f32x4){0.f, 0.f, 0.f, 0.f};
; #pragma unroll
;     for (int pp = 0; pp < 5; ++pp) { const int ktA = 2 * pp, ktB = 2 * pp + 1, ktBc = ktB < 9 ? ktB : 8;
;         union { bf16x8 v; unsigned u[4]; } pf;
;         pf.u[0] = cvt_pk_bf16(sc[ktA][0], sc[ktA][1]); pf.u[1] = cvt_pk_bf16(sc[ktA][2], sc[ktA][3]);
;         if (ktB < 9) { pf.u[2] = cvt_pk_bf16(sc[ktBc][0], sc[ktBc][1]); pf.u[3] = cvt_pk_bf16(sc[ktBc][2], sc[ktBc][3]); } else { pf.u[2] = 0u; pf.u[3] = 0u; }
; #pragma unroll
;         for (int dt = 0; dt < 4; ++dt) { const bf16_t* vr = Vs + (16 * w + 4 * quad + (fr >> 2)) * 72 + 16 * dt + 4 * (fr & 3);
;             union { bf16x8 v; s16x4_t h[2]; } vf; vf.h[0] = lds_tr_b64(vr + 16 * ktA * 72); vf.h[1] = lds_tr_b64(vr + 16 * ktBc * 72);
;             oo[dt] = __builtin_amdgcn_mfma_f32_16x16x32_bf16(vf.v, pf.v, oo[dt], 0, 0, 0); } }
;     const float inv = 1.0f / lsum;
;     const size_t tok = (size_t)(b * SEQ + r + dil * (128 * jb + a));
;     __syncthreads();
; #pragma unroll
;     for (int dt = 0; dt < 4; ++dt) { u32x2 o; o.x = cvt_pk_bf16(oo[dt][0] * inv, oo[dt][1] * inv); o.y = cvt_pk_bf16(oo[dt][2] * inv, oo[dt][3] * inv);
;         *(u32x2*)(pd + tok * 2304 + hq * 64 + 16 * dt + 4 * quad) = o; }
;     if (quad == 0) C.fp(OFF_LSE)[((size_t)g * M_TOK + tok) * 4 + (hq & 3)] = mx + __logf(lsum);
	v_mfma_f32_16x16x32_bf16 v[56:59], v[70:73], v[52:55], v[56:59]
	ds_read_b64_tr_b16 v[70:71], v172 offset:13856
	ds_read_b64_tr_b16 v[72:73], v172 offset:16160
	v_sub_f32_e32 v46, v46, v42
	v_mul_f32_e32 v46, 0x3fb8aa3b, v46
	v_sub_f32_e32 v47, v51, v42
	v_exp_f32_e32 v46, v46
	v_mul_f32_e32 v47, 0x3fb8aa3b, v47
	v_exp_f32_e32 v47, v47
	s_waitcnt lgkmcnt(0)
	v_mfma_f32_16x16x32_bf16 v[66:69], v[70:73], v[52:55], v[66:69]
	ds_read_b64_tr_b16 v[70:71], v172 offset:13888
	ds_read_b64_tr_b16 v[72:73], v172 offset:16192
	s_waitcnt lgkmcnt(0)
	v_mfma_f32_16x16x32_bf16 v[70:73], v[70:73], v[52:55], v[74:77]
	v_sub_f32_e32 v41, v41, v42
	v_mul_f32_e32 v41, 0x3fb8aa3b, v41
	v_exp_f32_e32 v41, v41
	ds_read_b64_tr_b16 v[74:75], v172 offset:13920
	ds_read_b64_tr_b16 v[76:77], v172 offset:16224
	v_add_f32_e32 v44, v45, v44
	v_add_f32_e32 v44, v46, v44
	v_mov_b32_e32 v48, v41
	v_add_f32_e32 v44, v47, v44
	s_waitcnt lgkmcnt(0)
	v_mfma_f32_16x16x32_bf16 v[50:53], v[74:77], v[52:55], v[60:63]
	v_add_f32_e32 v41, v48, v44
	ds_bpermute_b32 v44, v169, v41
	ds_read_b64_tr_b16 v[54:55], v172 offset:18464
	v_cvt_pk_bf16_f32 v62, v45, v46
	v_cvt_pk_bf16_f32 v63, v47, v48
	ds_read_b64_tr_b16 v[46:47], v172 offset:18432
	s_waitcnt lgkmcnt(2)
	v_add_f32_e32 v41, v41, v44
	ds_bpermute_b32 v44, v170, v41
	s_lshl_b32 s1, s51, 12
	s_or_b32 s0, s0, s1
	s_waitcnt lgkmcnt(1)
	v_mov_b32_e32 v48, v46
	v_mov_b32_e32 v49, v47
	s_waitcnt lgkmcnt(0)
	v_add_f32_e32 v41, v41, v44
	v_div_scale_f32 v40, s[48:49], v41, v41, 1.0
	v_mfma_f32_16x16x32_bf16 v[46:49], v[46:49], v[62:65], v[56:59]
	v_rcp_f32_e32 v43, v40
	s_nop 1
	v_mov_b32_e32 v56, v54
	v_mov_b32_e32 v57, v55
	ds_read_b64_tr_b16 v[58:59], v172 offset:18496
	v_fma_f32 v44, -v40, v43, 1.0
	v_mfma_f32_16x16x32_bf16 v[54:57], v[54:57], v[62:65], v[66:69]
	v_fmac_f32_e32 v43, v44, v43
	s_nop 1
	ds_read_b64_tr_b16 v[66:67], v172 offset:18528
	s_waitcnt lgkmcnt(1)
	v_mov_b32_e32 v60, v58
	v_mov_b32_e32 v61, v59
	v_div_scale_f32 v44, vcc, 1.0, v41, 1.0
	s_waitcnt lgkmcnt(0)
	v_mov_b32_e32 v68, v66
	v_mov_b32_e32 v69, v67
	v_mul_f32_e32 v45, v44, v43
	v_mfma_f32_16x16x32_bf16 v[58:61], v[58:61], v[62:65], v[70:73]
	s_barrier
	v_mfma_f32_16x16x32_bf16 v[50:53], v[66:69], v[62:65], v[50:53]
	v_fma_f32 v62, -v40, v45, v44
	v_fmac_f32_e32 v45, v62, v43
	v_fma_f32 v40, -v40, v45, v44
	v_div_fmas_f32 v40, v40, v43, v45
	v_div_fixup_f32 v44, v40, v41, 1.0
	v_add_u32_e32 v40, s46, v83
	v_lshlrev_b32_e32 v40, s52, v40
	v_add_u32_e32 v40, s0, v40
	v_mov_b64_e32 v[62:63], s[42:43]
	v_mad_i64_i32 v[62:63], s[0:1], v40, s66, v[62:63]
	s_lshl_b32 s0, s41, 6
	s_ashr_i32 s1, s0, 31
	v_lshl_add_u64 v[62:63], s[0:1], 1, v[62:63]
	v_pk_mul_f32 v[46:47], v[44:45], v[46:47] op_sel_hi:[0,1]
	v_pk_mul_f32 v[48:49], v[44:45], v[48:49] op_sel_hi:[0,1]
	v_lshl_add_u64 v[62:63], v[62:63], 0, v[90:91]
	v_cvt_pk_bf16_f32 v46, v46, v47
	v_cvt_pk_bf16_f32 v47, v48, v49
	global_store_dwordx2 v[62:63], v[46:47], off
	v_pk_mul_f32 v[46:47], v[44:45], v[54:55] op_sel_hi:[0,1]
	v_pk_mul_f32 v[48:49], v[44:45], v[56:57] op_sel_hi:[0,1]
	v_cvt_pk_bf16_f32 v46, v46, v47
	v_cvt_pk_bf16_f32 v47, v48, v49
	global_store_dwordx2 v[62:63], v[46:47], off offset:32
	v_pk_mul_f32 v[46:47], v[44:45], v[58:59] op_sel_hi:[0,1]
	v_pk_mul_f32 v[48:49], v[44:45], v[60:61] op_sel_hi:[0,1]
	v_cvt_pk_bf16_f32 v46, v46, v47
	v_cvt_pk_bf16_f32 v47, v48, v49
	global_store_dwordx2 v[62:63], v[46:47], off offset:64
	v_pk_mul_f32 v[46:47], v[44:45], v[50:51] op_sel_hi:[0,1]
	v_pk_mul_f32 v[44:45], v[44:45], v[52:53] op_sel_hi:[0,1]
	v_cvt_pk_bf16_f32 v46, v46, v47
	v_cvt_pk_bf16_f32 v47, v44, v45
	global_store_dwordx2 v[62:63], v[46:47], off offset:96
	s_and_saveexec_b64 s[0:1], s[20:21]
	s_cbranch_execz .LBB0_344
	v_cmp_gt_f32_e32 vcc, s54, v41
	s_ashr_i32 s41, s40, 31
	s_lshl_b64 s[40:41], s[40:41], 19
	v_cndmask_b32_e64 v43, 0, 32, vcc
	v_ldexp_f32 v41, v41, v43
	v_log_f32_e32 v43, v41
	v_readlane_b32 s46, v255, 43
	v_cndmask_b32_e32 v44, 0, v225, vcc
	s_add_u32 s40, s46, s40
	v_mul_f32_e32 v45, 0x3f317217, v43
	v_fma_f32 v45, v43, s56, -v45
	v_fmac_f32_e32 v45, 0x3377d1cf, v43
	v_fmac_f32_e32 v45, 0x3f317217, v43
	v_cmp_lt_f32_e64 vcc, |v43|, s57
	v_readlane_b32 s46, v255, 44
	v_ashrrev_i32_e32 v41, 31, v40
	v_cndmask_b32_e32 v43, v43, v45, vcc
	s_addc_u32 s41, s46, s41
	s_lshr_b32 s36, s36, 3
	v_sub_f32_e32 v43, v43, v44
	v_lshl_add_u64 v[40:41], v[40:41], 4, s[40:41]
	s_and_b32 s36, s36, 12
	v_add_f32_e32 v42, v42, v43
	v_lshl_add_u64 v[40:41], v[40:41], 0, s[36:37]
	global_store_dword v[40:41], v42, off
	s_branch .LBB0_344
